# attention: static priority raise of waves 4-7 removed (A/B)
# speedup vs baseline: 1.0069x; 1.0027x over previous
.LBB0_819:
	s_setprio 0
	s_mov_b64 s[6:7], -1
	s_and_b64 vcc, exec, s[4:5]
	s_cbranch_vccz .LBB0_768

.LBB0_833:
	ds_read_b64_tr_b16 v[76:77], v147 offset:49152
	ds_read_b64_tr_b16 v[78:79], v147 offset:49664
	v_cvt_pk_bf16_f32 v68, v68, v69
	v_cvt_pk_bf16_f32 v69, v70, v71
	v_cvt_pk_bf16_f32 v70, v72, v73
	v_cvt_pk_bf16_f32 v71, v74, v75
	s_waitcnt lgkmcnt(0)
	v_mfma_f32_32x32x16_bf16 v[18:33], v[164:167], v[76:79], v[18:33]
	ds_read_b64_tr_b16 v[76:77], v147 offset:50176
	ds_read_b64_tr_b16 v[78:79], v147 offset:50688
	v_add_f32_e32 v67, v213, v67
	s_waitcnt lgkmcnt(0)
	v_mfma_f32_32x32x16_bf16 v[18:33], v[168:171], v[76:79], v[18:33]
	ds_read_b64_tr_b16 v[76:77], v147 offset:51200
	ds_read_b64_tr_b16 v[78:79], v147 offset:51712
	ds_read_b64_tr_b16 v[80:81], v147 offset:52224
	ds_read_b64_tr_b16 v[82:83], v147 offset:52736
	ds_read_b64_tr_b16 v[72:73], v147 offset:53248
	ds_read_b64_tr_b16 v[74:75], v147 offset:53760
	s_waitcnt lgkmcnt(0)
	v_mfma_f32_32x32x16_bf16 v[50:65], v[164:167], v[72:75], v[50:65]
	ds_read_b64_tr_b16 v[72:73], v147 offset:54272
	ds_read_b64_tr_b16 v[74:75], v147 offset:54784
	s_waitcnt lgkmcnt(0)
	v_mfma_f32_32x32x16_bf16 v[50:65], v[168:171], v[72:75], v[50:65]
	ds_read_b64_tr_b16 v[72:73], v147 offset:55296
	ds_read_b64_tr_b16 v[74:75], v147 offset:55808
	s_waitcnt lgkmcnt(0)
	v_mfma_f32_32x32x16_bf16 v[50:65], v[172:175], v[72:75], v[50:65]
	ds_read_b64_tr_b16 v[72:73], v147 offset:56320
	ds_read_b64_tr_b16 v[74:75], v147 offset:56832
	v_mfma_f32_32x32x16_bf16 v[18:33], v[172:175], v[76:79], v[18:33]
	v_add_u32_e32 v76, 0xe000, v147
	s_waitcnt lgkmcnt(0)
	v_mfma_f32_32x32x16_bf16 v[50:65], v[68:71], v[72:75], v[50:65]
	ds_read_b64_tr_b16 v[72:73], v76 offset:24576
	ds_read_b64_tr_b16 v[74:75], v76 offset:25088
	s_waitcnt lgkmcnt(0)
	v_mfma_f32_32x32x16_bf16 v[34:49], v[164:167], v[72:75], v[34:49]
	ds_read_b64_tr_b16 v[72:73], v76 offset:25600
	ds_read_b64_tr_b16 v[74:75], v76 offset:26112
	s_waitcnt lgkmcnt(0)
	v_mfma_f32_32x32x16_bf16 v[34:49], v[168:171], v[72:75], v[34:49]
	ds_read_b64_tr_b16 v[72:73], v76 offset:26624
	ds_read_b64_tr_b16 v[74:75], v76 offset:27136
	s_waitcnt lgkmcnt(0)
	v_mfma_f32_32x32x16_bf16 v[34:49], v[172:175], v[72:75], v[34:49]
	ds_read_b64_tr_b16 v[72:73], v76 offset:27648
	ds_read_b64_tr_b16 v[74:75], v76 offset:28160
	s_waitcnt lgkmcnt(0)
	v_mfma_f32_32x32x16_bf16 v[34:49], v[68:71], v[72:75], v[34:49]
	ds_read_b64_tr_b16 v[72:73], v76 offset:28672
	ds_read_b64_tr_b16 v[74:75], v76 offset:29184
	s_waitcnt lgkmcnt(0)
	v_mfma_f32_32x32x16_bf16 v[2:17], v[164:167], v[72:75], v[2:17]
	ds_read_b64_tr_b16 v[72:73], v76 offset:29696
	ds_read_b64_tr_b16 v[74:75], v76 offset:30208
	s_waitcnt lgkmcnt(0)
	v_mfma_f32_32x32x16_bf16 v[2:17], v[168:171], v[72:75], v[2:17]
	ds_read_b64_tr_b16 v[72:73], v76 offset:30720
	ds_read_b64_tr_b16 v[74:75], v76 offset:31232
	s_waitcnt lgkmcnt(0)
	v_mfma_f32_32x32x16_bf16 v[2:17], v[172:175], v[72:75], v[2:17]
	ds_read_b64_tr_b16 v[72:73], v76 offset:31744
	ds_read_b64_tr_b16 v[74:75], v76 offset:32256
	v_mfma_f32_32x32x16_bf16 v[18:33], v[68:71], v[80:83], v[18:33]
	s_waitcnt lgkmcnt(0)
	v_mfma_f32_32x32x16_bf16 v[2:17], v[68:71], v[72:75], v[2:17]
	s_setprio 0
	v_mov_b32_e32 v68, v67
	s_nop 1
	v_permlane32_swap_b32_e32 v67, v68
	v_cmp_gt_u32_e32 vcc, 32, v207
	s_and_saveexec_b64 s[4:5], vcc
	v_add_f32_e32 v67, v67, v68
	ds_write_b32 v1, v67 offset:128
	s_or_b64 exec, exec, s[4:5]
	s_waitcnt lgkmcnt(0)
	ds_read_b128 v[68:71], v66 offset:128
	ds_read_b128 v[72:75], v66 offset:160
	s_mov_b64 s[4:5], s[0:1]
	s_lshl_b32 s12, s12, 12
	s_lshl_b64 s[8:9], s[80:81], 1
	s_waitcnt lgkmcnt(1)
	v_rcp_f32_e32 v1, v68
	v_rcp_f32_e32 v67, v69
	v_rcp_f32_e32 v76, v70
	v_rcp_f32_e32 v77, v71
	s_waitcnt lgkmcnt(0)
	v_rcp_f32_e32 v78, v72
	ds_read_b128 v[68:71], v66 offset:192
	v_rcp_f32_e32 v79, v73
	v_rcp_f32_e32 v80, v74
	v_rcp_f32_e32 v81, v75
	ds_read_b128 v[72:75], v66 offset:224
	s_load_dwordx2 s[4:5], s[4:5], 0xa0
	s_waitcnt lgkmcnt(0)
	v_rcp_f32_e32 v66, v68
	v_rcp_f32_e32 v68, v69
	v_rcp_f32_e32 v69, v70
	v_rcp_f32_e32 v70, v71
	s_add_u32 s4, s4, s8
	s_addc_u32 s5, s5, s9
	s_add_u32 s4, s4, s64
	s_addc_u32 s5, s5, s65
	s_add_i32 s8, s12, 0
	v_mul_f32_e32 v18, v18, v1
	v_mul_f32_e32 v50, v50, v1
	v_mul_f32_e32 v34, v34, v1
	v_mul_f32_e32 v1, v2, v1
	v_mul_f32_e32 v19, v19, v67
	v_mul_f32_e32 v51, v51, v67
	v_mul_f32_e32 v35, v35, v67
	v_mul_f32_e32 v67, v3, v67
	s_add_i32 s8, s8, 0x16800
	v_lshlrev_b32_e32 v2, 9, v209
	v_lshlrev_b32_e32 v3, 1, v208
	v_rcp_f32_e32 v71, v72
	v_rcp_f32_e32 v72, v73
	v_rcp_f32_e32 v73, v74
	v_rcp_f32_e32 v74, v75
	v_mul_f32_e32 v75, v4, v76
	v_mul_f32_e32 v4, v21, v77
	v_mul_f32_e32 v21, v53, v77
	v_mul_f32_e32 v53, v5, v77
	v_mul_f32_e32 v5, v22, v78
	v_mul_f32_e32 v22, v54, v78
	v_mul_f32_e32 v54, v6, v78
	v_mul_f32_e32 v6, v23, v79
	v_mul_f32_e32 v23, v55, v79
	v_mul_f32_e32 v55, v7, v79
	v_mul_f32_e32 v7, v24, v80
	v_mul_f32_e32 v24, v56, v80
	v_mul_f32_e32 v56, v8, v80
	v_mul_f32_e32 v8, v25, v81
	v_mul_f32_e32 v25, v57, v81
	v_mul_f32_e32 v57, v9, v81
	v_mul_f32_e32 v9, v26, v66
	v_mul_f32_e32 v26, v58, v66
	v_mul_f32_e32 v42, v42, v66
	v_mul_f32_e32 v58, v10, v66
	v_mul_f32_e32 v27, v27, v68
	v_mul_f32_e32 v59, v59, v68
	v_mul_f32_e32 v43, v43, v68
	v_mul_f32_e32 v66, v11, v68
	v_add3_u32 v68, s8, v2, v3
	v_lshlrev_b32_e32 v2, 1, v210
	v_and_b32_e32 v2, 0x70, v2
	v_mov_b32_e32 v3, v146
	v_mul_f32_e32 v29, v29, v70
	v_mul_f32_e32 v61, v61, v70
	v_mul_f32_e32 v45, v45, v70
	v_mul_f32_e32 v13, v13, v70
	v_add_u32_e32 v70, s8, v2
	v_lshl_add_u64 v[2:3], s[4:5], 0, v[2:3]
	v_lshl_add_u64 v[10:11], v[2:3], 0, s[86:87]
	v_cvt_pk_bf16_f32 v2, v18, s0
	ds_write_b16 v68, v2
	v_cvt_pk_bf16_f32 v2, v50, s0
	ds_write_b16 v68, v2 offset:64
	v_cvt_pk_bf16_f32 v2, v19, s0
	v_mul_f32_e32 v20, v20, v76
	ds_write_b16 v68, v2 offset:128
	v_cvt_pk_bf16_f32 v2, v51, s0
	v_mul_f32_e32 v52, v52, v76
	ds_write_b16 v68, v2 offset:192
	v_cvt_pk_bf16_f32 v2, v20, s0
	ds_write_b16 v68, v2 offset:256
	v_cvt_pk_bf16_f32 v2, v52, s0
	ds_write_b16 v68, v2 offset:320
	v_cvt_pk_bf16_f32 v2, v4, s0
	ds_write_b16 v68, v2 offset:384
	v_cvt_pk_bf16_f32 v2, v21, s0
	ds_write_b16 v68, v2 offset:448
	v_cvt_pk_bf16_f32 v2, v5, s0
	ds_write_b16 v68, v2 offset:1024
	v_cvt_pk_bf16_f32 v2, v22, s0
	ds_write_b16 v68, v2 offset:1088
	v_cvt_pk_bf16_f32 v2, v6, s0
	ds_write_b16 v68, v2 offset:1152
	v_cvt_pk_bf16_f32 v2, v23, s0
	ds_write_b16 v68, v2 offset:1216
	v_cvt_pk_bf16_f32 v2, v7, s0
	ds_write_b16 v68, v2 offset:1280
	v_cvt_pk_bf16_f32 v2, v24, s0
	ds_write_b16 v68, v2 offset:1344
	v_cvt_pk_bf16_f32 v2, v8, s0
	ds_write_b16 v68, v2 offset:1408
	v_cvt_pk_bf16_f32 v2, v25, s0
	ds_write_b16 v68, v2 offset:1472
	v_cvt_pk_bf16_f32 v2, v9, s0
	ds_write_b16 v68, v2 offset:2048
	v_cvt_pk_bf16_f32 v2, v26, s0
	ds_write_b16 v68, v2 offset:2112
	v_cvt_pk_bf16_f32 v2, v27, s0
	v_mul_f32_e32 v28, v28, v69
	ds_write_b16 v68, v2 offset:2176
	v_cvt_pk_bf16_f32 v2, v59, s0
	v_mul_f32_e32 v60, v60, v69
	ds_write_b16 v68, v2 offset:2240
	v_cvt_pk_bf16_f32 v2, v28, s0
	ds_write_b16 v68, v2 offset:2304
	v_cvt_pk_bf16_f32 v2, v60, s0
	ds_write_b16 v68, v2 offset:2368
	v_cvt_pk_bf16_f32 v2, v29, s0
	v_mul_f32_e32 v30, v30, v71
	ds_write_b16 v68, v2 offset:2432
	v_cvt_pk_bf16_f32 v2, v61, s0
	v_mul_f32_e32 v62, v62, v71
	ds_write_b16 v68, v2 offset:2496
	v_cvt_pk_bf16_f32 v2, v30, s0
	v_mul_f32_e32 v31, v31, v72
	ds_write_b16 v68, v2 offset:3072
	v_cvt_pk_bf16_f32 v2, v62, s0
	v_mul_f32_e32 v63, v63, v72
	ds_write_b16 v68, v2 offset:3136
	v_cvt_pk_bf16_f32 v2, v31, s0
	v_mul_f32_e32 v32, v32, v73
	ds_write_b16 v68, v2 offset:3200
	v_cvt_pk_bf16_f32 v2, v63, s0
	v_mul_f32_e32 v64, v64, v73
	ds_write_b16 v68, v2 offset:3264
	v_cvt_pk_bf16_f32 v2, v32, s0
	v_mul_f32_e32 v33, v33, v74
	ds_write_b16 v68, v2 offset:3328
	v_cvt_pk_bf16_f32 v2, v64, s0
	v_mul_f32_e32 v65, v65, v74
	ds_write_b16 v68, v2 offset:3392
	v_cvt_pk_bf16_f32 v2, v33, s0
	ds_write_b16 v68, v2 offset:3456
	v_cvt_pk_bf16_f32 v2, v65, s0
	v_mul_f32_e32 v44, v44, v69
	v_mul_f32_e32 v12, v12, v69
	v_lshrrev_b32_e32 v69, 3, v207
	ds_write_b16 v68, v2 offset:3520
	v_mul_f32_e32 v46, v46, v71
	v_mul_f32_e32 v14, v14, v71
	v_lshl_add_u32 v71, v69, 7, v70
	s_waitcnt lgkmcnt(0)
	ds_read_b128 v[2:5], v71
	v_or_b32_e32 v20, 8, v69
	v_lshlrev_b32_e32 v6, 11, v69
	v_mov_b32_e32 v7, v146
	v_lshl_add_u32 v26, v20, 7, v70
	v_lshl_add_u64 v[18:19], v[10:11], 0, v[6:7]
	ds_read_b128 v[6:9], v26
	s_waitcnt lgkmcnt(1)
	global_store_dwordx4 v[18:19], v[2:5], off
	v_or_b32_e32 v24, 24, v69
	v_lshl_add_u32 v28, v24, 7, v70
	v_lshlrev_b32_e32 v2, 11, v20
	v_mov_b32_e32 v3, v146
	v_lshl_add_u64 v[20:21], v[10:11], 0, v[2:3]
	s_waitcnt lgkmcnt(0)
	global_store_dwordx4 v[20:21], v[6:9], off
	v_cvt_pk_bf16_f32 v1, v1, s0
	v_mul_f32_e32 v36, v36, v76
	v_or_b32_e32 v6, 16, v69
	v_lshl_add_u32 v27, v6, 7, v70
	ds_read_b128 v[2:5], v27
	v_lshlrev_b32_e32 v6, 11, v6
	v_mov_b32_e32 v7, v146
	v_lshl_add_u64 v[22:23], v[10:11], 0, v[6:7]
	ds_read_b128 v[6:9], v28
	s_waitcnt lgkmcnt(1)
	global_store_dwordx4 v[22:23], v[2:5], off
	v_mul_f32_e32 v37, v37, v77
	v_mul_f32_e32 v38, v38, v78
	v_lshlrev_b32_e32 v2, 11, v24
	v_mov_b32_e32 v3, v146
	v_lshl_add_u64 v[24:25], v[10:11], 0, v[2:3]
	s_waitcnt lgkmcnt(0)
	global_store_dwordx4 v[24:25], v[6:9], off
	s_waitcnt lgkmcnt(0)
	ds_write_b16 v68, v1 offset:64
	v_cvt_pk_bf16_f32 v1, v35, s0
	ds_write_b16 v68, v1 offset:128
	v_cvt_pk_bf16_f32 v1, v67, s0
	ds_write_b16 v68, v1 offset:192
	v_cvt_pk_bf16_f32 v1, v36, s0
	ds_write_b16 v68, v1 offset:256
	v_cvt_pk_bf16_f32 v1, v75, s0
	ds_write_b16 v68, v1 offset:320
	v_cvt_pk_bf16_f32 v1, v37, s0
	ds_write_b16 v68, v1 offset:384
	v_cvt_pk_bf16_f32 v1, v53, s0
	ds_write_b16 v68, v1 offset:448
	v_cvt_pk_bf16_f32 v1, v38, s0
	v_mul_f32_e32 v39, v39, v79
	ds_write_b16 v68, v1 offset:1024
	v_cvt_pk_bf16_f32 v1, v54, s0
	ds_write_b16 v68, v1 offset:1088
	v_cvt_pk_bf16_f32 v1, v39, s0
	v_mul_f32_e32 v40, v40, v80
	ds_write_b16 v68, v1 offset:1152
	v_cvt_pk_bf16_f32 v1, v55, s0
	ds_write_b16 v68, v1 offset:1216
	v_cvt_pk_bf16_f32 v1, v40, s0
	v_mul_f32_e32 v41, v41, v81
	ds_write_b16 v68, v1 offset:1280
	v_cvt_pk_bf16_f32 v1, v56, s0
	ds_write_b16 v68, v1 offset:1344
	v_cvt_pk_bf16_f32 v1, v41, s0
	ds_write_b16 v68, v1 offset:1408
	v_cvt_pk_bf16_f32 v1, v57, s0
	ds_write_b16 v68, v1 offset:1472
	v_cvt_pk_bf16_f32 v1, v42, s0
	ds_write_b16 v68, v1 offset:2048
	v_cvt_pk_bf16_f32 v1, v58, s0
	ds_write_b16 v68, v1 offset:2112
	v_cvt_pk_bf16_f32 v1, v43, s0
	ds_write_b16 v68, v1 offset:2176
	v_cvt_pk_bf16_f32 v1, v66, s0
	ds_write_b16 v68, v1 offset:2240
	v_cvt_pk_bf16_f32 v1, v44, s0
	ds_write_b16 v68, v1 offset:2304
	v_cvt_pk_bf16_f32 v1, v12, s0
	ds_write_b16 v68, v1 offset:2368
	v_cvt_pk_bf16_f32 v1, v45, s0
	ds_write_b16 v68, v1 offset:2432
	v_cvt_pk_bf16_f32 v1, v13, s0
	ds_write_b16 v68, v1 offset:2496
	v_cvt_pk_bf16_f32 v1, v46, s0
	v_mul_f32_e32 v47, v47, v72
	ds_write_b16 v68, v1 offset:3072
	v_cvt_pk_bf16_f32 v1, v14, s0
	v_mul_f32_e32 v15, v15, v72
	ds_write_b16 v68, v1 offset:3136
	v_cvt_pk_bf16_f32 v1, v47, s0
	v_mul_f32_e32 v48, v48, v73
	ds_write_b16 v68, v1 offset:3200
	v_cvt_pk_bf16_f32 v1, v15, s0
	v_mul_f32_e32 v16, v16, v73
	ds_write_b16 v68, v1 offset:3264
	v_cvt_pk_bf16_f32 v1, v48, s0
	v_mul_f32_e32 v49, v49, v74
	ds_write_b16 v68, v1 offset:3328
	v_cvt_pk_bf16_f32 v1, v16, s0
	v_mul_f32_e32 v17, v17, v74
	ds_write_b16 v68, v1 offset:3392
	v_cvt_pk_bf16_f32 v1, v49, s0
	v_cvt_pk_bf16_f32 v2, v34, s0
	ds_write_b16 v68, v1 offset:3456
	v_cvt_pk_bf16_f32 v1, v17, s0
	ds_write_b16 v68, v2
	ds_write_b16 v68, v1 offset:3520
	s_waitcnt lgkmcnt(0)
	ds_read_b128 v[2:5], v71
	ds_read_b128 v[6:9], v26
	ds_read_b128 v[10:13], v27
	ds_read_b128 v[14:17], v28
	s_waitcnt lgkmcnt(3)
	global_store_dwordx4 v[18:19], v[2:5], off offset:128
	s_waitcnt lgkmcnt(2)
	global_store_dwordx4 v[20:21], v[6:9], off offset:128
	s_waitcnt lgkmcnt(1)
	global_store_dwordx4 v[22:23], v[10:13], off offset:128
	s_waitcnt lgkmcnt(0)
	global_store_dwordx4 v[24:25], v[14:17], off offset:128
	s_waitcnt lgkmcnt(0)
	s_waitcnt vmcnt(0)
	s_mov_b64 s[4:5], s[0:1]
	s_waitcnt lgkmcnt(0)
	s_barrier
	s_load_dwordx2 s[22:23], s[4:5], 0xa0
	v_mov_b32_e32 v34, v202
	v_mov_b32_e32 v2, v0
	v_readfirstlane_b32 s14, v34
	v_mov_b32_e32 v3, v0
	v_mov_b32_e32 v4, v0
	v_mov_b32_e32 v5, v0
	v_mov_b32_e32 v6, v0
	v_mov_b32_e32 v7, v0
	v_mov_b32_e32 v8, v0
	v_mov_b32_e32 v9, v0
	v_mov_b32_e32 v10, v0
	v_mov_b32_e32 v11, v0
	v_mov_b32_e32 v12, v0
	v_mov_b32_e32 v13, v0
	v_mov_b32_e32 v14, v0
	v_mov_b32_e32 v15, v0
	s_ashr_i32 s12, s14, 6
	v_mov_b32_e32 v1, v0
	v_mov_b64_e32 v[16:17], v[14:15]
	v_mov_b64_e32 v[14:15], v[12:13]
	v_mov_b64_e32 v[12:13], v[10:11]
	v_mov_b64_e32 v[10:11], v[8:9]
	v_mov_b64_e32 v[8:9], v[6:7]
	v_mov_b64_e32 v[6:7], v[4:5]
	v_mov_b64_e32 v[4:5], v[2:3]
	v_mov_b64_e32 v[2:3], v[0:1]
	s_cmp_lt_i32 s12, 4
	s_cbranch_scc1 .LBB0_837
	s_setprio 0
